# v25: GU epilogue blocks 1-7 store address = block 0 address + row_delta*stride (1 64-bit add instead of mad_i64 + 3 adds)
# speedup vs baseline: 1.0056x; 1.0056x over previous
; #define PG8_LAS __attribute__((address_space(3)))
; __device__ __forceinline__ u32x4 pack8(const f32x4 a, const f32x4 b) { u32x4 w; w.x = cvt_pk_bf16(a[0], a[1]); w.y = cvt_pk_bf16(a[2], a[3]); w.z = cvt_pk_bf16(b[0], b[1]); w.w = cvt_pk_bf16(b[2], b[3]); return w; }
;     __device__ __forceinline__ void operator()(const f32x4 (&acc)[2][2][4][2], const Unit& u, int wr, int wc, int fr, int fq) const {
;         PG8_LAS const float* R = stage_rstd((const float*)(ws + WS_PS), lds, u.pm);
; #pragma unroll
;         for (int ai = 0; ai < 2; ++ai)
; #pragma unroll
;             for (int m = 0; m < 4; ++m) {
;                 const int row = u.pm * BM + ai * HALF + wr * 64 + m * 16 + fr;
;                 const float rs = R[ai * HALF + wr * 64 + m * 16 + fr];
;                 bf16_t* ACT = (bf16_t*)(ws + WS_ACT);
;                 f32x4 a[2];
; #pragma unroll
;                 for (int n = 0; n < 2; ++n) {
;                     const f32x4 g = acc[ai][0][m][n] * rs, uu = acc[ai][1][m][n] * rs;
; #pragma unroll
;                     for (int j = 0; j < 4; ++j) a[n][j] = g[j] * __builtin_amdgcn_rcpf(1.0f + __builtin_amdgcn_exp2f(-1.4426950408889634f * g[j])) * uu[j];
;                 }
;                 *(u32x4*)(ACT + (size_t)row * 2816 + u.pn * 128 + wc * 32 + 8 * fq) = pack8(a[0], a[1]);
;             }
.LBB0_38:
	s_lshl_b32 s3, s48, 8
	ds_read_b32 v146, v142
	v_mov_b32_e32 v145, 0xbfb8aa3b
	s_waitcnt lgkmcnt(0)
	v_pk_mul_f32 v[124:125], v[124:125], v[146:147] op_sel_hi:[1,0]
	v_pk_mul_f32 v[126:127], v[126:127], v[146:147] op_sel_hi:[1,0]
	v_pk_mul_f32 v[116:117], v[116:117], v[146:147] op_sel_hi:[1,0]
	v_pk_mul_f32 v[118:119], v[118:119], v[146:147] op_sel_hi:[1,0]
	v_pk_mul_f32 v[120:121], v[120:121], v[146:147] op_sel_hi:[1,0]
	v_pk_mul_f32 v[122:123], v[122:123], v[146:147] op_sel_hi:[1,0]
	v_pk_mul_f32 v[112:113], v[112:113], v[146:147] op_sel_hi:[1,0]
	v_pk_mul_f32 v[114:115], v[114:115], v[146:147] op_sel_hi:[1,0]
	v_pk_mul_f32 v[148:149], v[124:125], v[144:145] op_sel:[0,1] op_sel_hi:[1,1]
	v_exp_f32_e32 v148, v148
	v_exp_f32_e32 v149, v149
	v_add_f32_e32 v148, 1.0, v148
	v_add_f32_e32 v149, 1.0, v149
	v_rcp_f32_e32 v148, v148
	v_rcp_f32_e32 v149, v149
	s_nop 0
	v_pk_mul_f32 v[124:125], v[124:125], v[148:149]
	v_pk_mul_f32 v[120:121], v[120:121], v[124:125]
	v_pk_mul_f32 v[148:149], v[126:127], v[144:145] op_sel:[0,1] op_sel_hi:[1,1]
	v_exp_f32_e32 v148, v148
	v_exp_f32_e32 v149, v149
	v_add_f32_e32 v148, 1.0, v148
	v_add_f32_e32 v149, 1.0, v149
	v_rcp_f32_e32 v148, v148
	v_rcp_f32_e32 v149, v149
	s_nop 0
	v_pk_mul_f32 v[126:127], v[126:127], v[148:149]
	v_pk_mul_f32 v[122:123], v[122:123], v[126:127]
	v_pk_mul_f32 v[148:149], v[116:117], v[144:145] op_sel:[0,1] op_sel_hi:[1,1]
	v_exp_f32_e32 v148, v148
	v_exp_f32_e32 v149, v149
	v_add_f32_e32 v148, 1.0, v148
	v_add_f32_e32 v149, 1.0, v149
	v_rcp_f32_e32 v148, v148
	v_rcp_f32_e32 v149, v149
	s_nop 0
	v_pk_mul_f32 v[116:117], v[116:117], v[148:149]
	v_pk_mul_f32 v[112:113], v[112:113], v[116:117]
	v_pk_mul_f32 v[148:149], v[118:119], v[144:145] op_sel:[0,1] op_sel_hi:[1,1]
	v_exp_f32_e32 v148, v148
	v_exp_f32_e32 v149, v149
	v_add_f32_e32 v148, 1.0, v148
	v_add_f32_e32 v149, 1.0, v149
	v_rcp_f32_e32 v148, v148
	v_rcp_f32_e32 v149, v149
	s_nop 0
	v_pk_mul_f32 v[118:119], v[118:119], v[148:149]
	v_pk_mul_f32 v[114:115], v[114:115], v[118:119]
	v_cvt_pk_bf16_f32 v116, v112, v113
	v_cvt_pk_bf16_f32 v117, v114, v115
	v_cvt_pk_bf16_f32 v114, v120, v121
	v_cvt_pk_bf16_f32 v115, v122, v123
	s_lshl_b32 s0, s47, 7
	v_add_u32_e32 v144, s3, v140
	s_ashr_i32 s1, s0, 31
	s_movk_i32 s3, 0x1600
	s_lshl_b64 s[0:1], s[0:1], 1
	s_andn2_b64 vcc, exec, s[36:37]
	v_mov_b64_e32 v[112:113], s[16:17]
	s_mov_b32 s101, 0
	v_mad_i64_i32 v[118:119], s[4:5], v144, s3, v[112:113]
	v_lshl_add_u64 v[118:119], v[118:119], 0, s[0:1]
	v_lshl_add_u64 v[118:119], v[118:119], 0, s[34:35]
	v_lshl_add_u64 v[118:119], v[118:119], 0, v[184:185]
	global_store_dwordx4 v[118:119], v[114:117], off
	ds_read_b32 v114, v142 offset:64
	s_waitcnt lgkmcnt(0)
	v_pk_mul_f32 v[108:109], v[108:109], v[114:115] op_sel_hi:[1,0]
	v_pk_mul_f32 v[110:111], v[110:111], v[114:115] op_sel_hi:[1,0]
	v_pk_mul_f32 v[100:101], v[100:101], v[114:115] op_sel_hi:[1,0]
	v_pk_mul_f32 v[102:103], v[102:103], v[114:115] op_sel_hi:[1,0]
	v_pk_mul_f32 v[104:105], v[104:105], v[114:115] op_sel_hi:[1,0]
	v_pk_mul_f32 v[106:107], v[106:107], v[114:115] op_sel_hi:[1,0]
	v_pk_mul_f32 v[96:97], v[96:97], v[114:115] op_sel_hi:[1,0]
	v_pk_mul_f32 v[98:99], v[98:99], v[114:115] op_sel_hi:[1,0]
	v_pk_mul_f32 v[148:149], v[108:109], v[144:145] op_sel:[0,1] op_sel_hi:[1,1]
	v_exp_f32_e32 v148, v148
	v_exp_f32_e32 v149, v149
	v_add_f32_e32 v148, 1.0, v148
	v_add_f32_e32 v149, 1.0, v149
	v_rcp_f32_e32 v148, v148
	v_rcp_f32_e32 v149, v149
	s_nop 0
	v_pk_mul_f32 v[108:109], v[108:109], v[148:149]
	v_pk_mul_f32 v[104:105], v[104:105], v[108:109]
	v_pk_mul_f32 v[148:149], v[110:111], v[144:145] op_sel:[0,1] op_sel_hi:[1,1]
	v_exp_f32_e32 v148, v148
	v_exp_f32_e32 v149, v149
	v_add_f32_e32 v148, 1.0, v148
	v_add_f32_e32 v149, 1.0, v149
	v_rcp_f32_e32 v148, v148
	v_rcp_f32_e32 v149, v149
	s_nop 0
	v_pk_mul_f32 v[110:111], v[110:111], v[148:149]
	v_pk_mul_f32 v[106:107], v[106:107], v[110:111]
	v_pk_mul_f32 v[148:149], v[100:101], v[144:145] op_sel:[0,1] op_sel_hi:[1,1]
	v_exp_f32_e32 v148, v148
	v_exp_f32_e32 v149, v149
	v_add_f32_e32 v148, 1.0, v148
	v_add_f32_e32 v149, 1.0, v149
	v_rcp_f32_e32 v148, v148
	v_rcp_f32_e32 v149, v149
	s_nop 0
	v_pk_mul_f32 v[100:101], v[100:101], v[148:149]
	v_pk_mul_f32 v[96:97], v[96:97], v[100:101]
	v_pk_mul_f32 v[148:149], v[102:103], v[144:145] op_sel:[0,1] op_sel_hi:[1,1]
	v_exp_f32_e32 v148, v148
	v_exp_f32_e32 v149, v149
	v_add_f32_e32 v148, 1.0, v148
	v_add_f32_e32 v149, 1.0, v149
	v_rcp_f32_e32 v148, v148
	v_rcp_f32_e32 v149, v149
	s_nop 0
	v_pk_mul_f32 v[102:103], v[102:103], v[148:149]
	v_pk_mul_f32 v[98:99], v[98:99], v[102:103]
	v_cvt_pk_bf16_f32 v99, v98, v99
	v_cvt_pk_bf16_f32 v98, v96, v97
	v_cvt_pk_bf16_f32 v96, v104, v105
	v_cvt_pk_bf16_f32 v97, v106, v107
	s_mov_b32 s100, 0x16000
	v_lshl_add_u64 v[100:101], v[118:119], 0, s[100:101]
	global_store_dwordx4 v[100:101], v[96:99], off
	ds_read_b32 v96, v142 offset:128
	s_waitcnt lgkmcnt(0)
; __device__ __forceinline__ u32x4 pack8(const f32x4 a, const f32x4 b) { u32x4 w; w.x = cvt_pk_bf16(a[0], a[1]); w.y = cvt_pk_bf16(a[2], a[3]); w.z = cvt_pk_bf16(b[0], b[1]); w.w = cvt_pk_bf16(b[2], b[3]); return w; }
;     __device__ __forceinline__ void operator()(const f32x4 (&acc)[2][2][4][2], const Unit& u, int wr, int wc, int fr, int fq) const {
;     ...
;                 const int row = u.pm * BM + ai * HALF + wr * 64 + m * 16 + fr;
;                 const float rs = R[ai * HALF + wr * 64 + m * 16 + fr];
;                 bf16_t* ACT = (bf16_t*)(ws + WS_ACT);
;                 f32x4 a[2];
; #pragma unroll
;                 for (int n = 0; n < 2; ++n) {
;                     const f32x4 g = acc[ai][0][m][n] * rs, uu = acc[ai][1][m][n] * rs;
; #pragma unroll
;                     for (int j = 0; j < 4; ++j) a[n][j] = g[j] * __builtin_amdgcn_rcpf(1.0f + __builtin_amdgcn_exp2f(-1.4426950408889634f * g[j])) * uu[j];
;                 }
;                 *(u32x4*)(ACT + (size_t)row * 2816 + u.pn * 128 + wc * 32 + 8 * fq) = pack8(a[0], a[1]);
	v_pk_mul_f32 v[92:93], v[92:93], v[96:97] op_sel_hi:[1,0]
	v_pk_mul_f32 v[94:95], v[94:95], v[96:97] op_sel_hi:[1,0]
	v_pk_mul_f32 v[84:85], v[84:85], v[96:97] op_sel_hi:[1,0]
	v_pk_mul_f32 v[86:87], v[86:87], v[96:97] op_sel_hi:[1,0]
	v_pk_mul_f32 v[88:89], v[88:89], v[96:97] op_sel_hi:[1,0]
	v_pk_mul_f32 v[90:91], v[90:91], v[96:97] op_sel_hi:[1,0]
	v_pk_mul_f32 v[80:81], v[80:81], v[96:97] op_sel_hi:[1,0]
	v_pk_mul_f32 v[82:83], v[82:83], v[96:97] op_sel_hi:[1,0]
	v_pk_mul_f32 v[148:149], v[92:93], v[144:145] op_sel:[0,1] op_sel_hi:[1,1]
	v_exp_f32_e32 v148, v148
	v_exp_f32_e32 v149, v149
	v_add_f32_e32 v148, 1.0, v148
	v_add_f32_e32 v149, 1.0, v149
	v_rcp_f32_e32 v148, v148
	v_rcp_f32_e32 v149, v149
	s_nop 0
	v_pk_mul_f32 v[92:93], v[92:93], v[148:149]
	v_pk_mul_f32 v[88:89], v[88:89], v[92:93]
	v_pk_mul_f32 v[148:149], v[94:95], v[144:145] op_sel:[0,1] op_sel_hi:[1,1]
	v_exp_f32_e32 v148, v148
	v_exp_f32_e32 v149, v149
	v_add_f32_e32 v148, 1.0, v148
	v_add_f32_e32 v149, 1.0, v149
	v_rcp_f32_e32 v148, v148
	v_rcp_f32_e32 v149, v149
	s_nop 0
	v_pk_mul_f32 v[94:95], v[94:95], v[148:149]
	v_pk_mul_f32 v[90:91], v[90:91], v[94:95]
	v_pk_mul_f32 v[148:149], v[84:85], v[144:145] op_sel:[0,1] op_sel_hi:[1,1]
	v_exp_f32_e32 v148, v148
	v_exp_f32_e32 v149, v149
	v_add_f32_e32 v148, 1.0, v148
	v_add_f32_e32 v149, 1.0, v149
	v_rcp_f32_e32 v148, v148
	v_rcp_f32_e32 v149, v149
	s_nop 0
	v_pk_mul_f32 v[84:85], v[84:85], v[148:149]
	v_pk_mul_f32 v[80:81], v[80:81], v[84:85]
	v_pk_mul_f32 v[148:149], v[86:87], v[144:145] op_sel:[0,1] op_sel_hi:[1,1]
	v_exp_f32_e32 v148, v148
	v_exp_f32_e32 v149, v149
	v_add_f32_e32 v148, 1.0, v148
	v_add_f32_e32 v149, 1.0, v149
	v_rcp_f32_e32 v148, v148
	v_rcp_f32_e32 v149, v149
	s_nop 0
	v_pk_mul_f32 v[86:87], v[86:87], v[148:149]
	v_pk_mul_f32 v[82:83], v[82:83], v[86:87]
	v_cvt_pk_bf16_f32 v83, v82, v83
	v_cvt_pk_bf16_f32 v82, v80, v81
	v_cvt_pk_bf16_f32 v80, v88, v89
	v_cvt_pk_bf16_f32 v81, v90, v91
	s_mov_b32 s100, 0x2c000
	v_lshl_add_u64 v[84:85], v[118:119], 0, s[100:101]
	global_store_dwordx4 v[84:85], v[80:83], off
	ds_read_b32 v80, v142 offset:192
	s_waitcnt lgkmcnt(0)
	v_pk_mul_f32 v[76:77], v[76:77], v[80:81] op_sel_hi:[1,0]
	v_pk_mul_f32 v[78:79], v[78:79], v[80:81] op_sel_hi:[1,0]
	v_pk_mul_f32 v[68:69], v[68:69], v[80:81] op_sel_hi:[1,0]
	v_pk_mul_f32 v[70:71], v[70:71], v[80:81] op_sel_hi:[1,0]
	v_pk_mul_f32 v[72:73], v[72:73], v[80:81] op_sel_hi:[1,0]
	v_pk_mul_f32 v[74:75], v[74:75], v[80:81] op_sel_hi:[1,0]
	v_pk_mul_f32 v[64:65], v[64:65], v[80:81] op_sel_hi:[1,0]
	v_pk_mul_f32 v[66:67], v[66:67], v[80:81] op_sel_hi:[1,0]
	v_pk_mul_f32 v[148:149], v[76:77], v[144:145] op_sel:[0,1] op_sel_hi:[1,1]
	v_exp_f32_e32 v148, v148
	v_exp_f32_e32 v149, v149
	v_add_f32_e32 v148, 1.0, v148
	v_add_f32_e32 v149, 1.0, v149
	v_rcp_f32_e32 v148, v148
	v_rcp_f32_e32 v149, v149
	s_nop 0
	v_pk_mul_f32 v[76:77], v[76:77], v[148:149]
	v_pk_mul_f32 v[72:73], v[72:73], v[76:77]
	v_pk_mul_f32 v[148:149], v[78:79], v[144:145] op_sel:[0,1] op_sel_hi:[1,1]
	v_exp_f32_e32 v148, v148
	v_exp_f32_e32 v149, v149
	v_add_f32_e32 v148, 1.0, v148
	v_add_f32_e32 v149, 1.0, v149
	v_rcp_f32_e32 v148, v148
	v_rcp_f32_e32 v149, v149
	s_nop 0
	v_pk_mul_f32 v[78:79], v[78:79], v[148:149]
	v_pk_mul_f32 v[74:75], v[74:75], v[78:79]
	v_pk_mul_f32 v[148:149], v[68:69], v[144:145] op_sel:[0,1] op_sel_hi:[1,1]
	v_exp_f32_e32 v148, v148
	v_exp_f32_e32 v149, v149
	v_add_f32_e32 v148, 1.0, v148
	v_add_f32_e32 v149, 1.0, v149
	v_rcp_f32_e32 v148, v148
	v_rcp_f32_e32 v149, v149
	s_nop 0
	v_pk_mul_f32 v[68:69], v[68:69], v[148:149]
	v_pk_mul_f32 v[64:65], v[64:65], v[68:69]
	v_pk_mul_f32 v[148:149], v[70:71], v[144:145] op_sel:[0,1] op_sel_hi:[1,1]
	v_exp_f32_e32 v148, v148
	v_exp_f32_e32 v149, v149
	v_add_f32_e32 v148, 1.0, v148
	v_add_f32_e32 v149, 1.0, v149
	v_rcp_f32_e32 v148, v148
	v_rcp_f32_e32 v149, v149
	s_nop 0
	v_pk_mul_f32 v[70:71], v[70:71], v[148:149]
	v_pk_mul_f32 v[66:67], v[66:67], v[70:71]
	v_cvt_pk_bf16_f32 v67, v66, v67
	v_cvt_pk_bf16_f32 v66, v64, v65
	v_cvt_pk_bf16_f32 v64, v72, v73
	v_cvt_pk_bf16_f32 v65, v74, v75
	s_mov_b32 s100, 0x42000
	v_lshl_add_u64 v[68:69], v[118:119], 0, s[100:101]
	global_store_dwordx4 v[68:69], v[64:67], off
	ds_read_b32 v64, v142 offset:512
	s_waitcnt lgkmcnt(0)
	v_pk_mul_f32 v[60:61], v[60:61], v[64:65] op_sel_hi:[1,0]
	v_pk_mul_f32 v[62:63], v[62:63], v[64:65] op_sel_hi:[1,0]
	v_pk_mul_f32 v[52:53], v[52:53], v[64:65] op_sel_hi:[1,0]
	v_pk_mul_f32 v[54:55], v[54:55], v[64:65] op_sel_hi:[1,0]
	v_pk_mul_f32 v[56:57], v[56:57], v[64:65] op_sel_hi:[1,0]
	v_pk_mul_f32 v[58:59], v[58:59], v[64:65] op_sel_hi:[1,0]
	v_pk_mul_f32 v[48:49], v[48:49], v[64:65] op_sel_hi:[1,0]
	v_pk_mul_f32 v[50:51], v[50:51], v[64:65] op_sel_hi:[1,0]
	v_pk_mul_f32 v[148:149], v[60:61], v[144:145] op_sel:[0,1] op_sel_hi:[1,1]
	v_exp_f32_e32 v148, v148
	v_exp_f32_e32 v149, v149
	v_add_f32_e32 v148, 1.0, v148
	v_add_f32_e32 v149, 1.0, v149
	v_rcp_f32_e32 v148, v148
	v_rcp_f32_e32 v149, v149
	s_nop 0
	v_pk_mul_f32 v[60:61], v[60:61], v[148:149]
	v_pk_mul_f32 v[56:57], v[56:57], v[60:61]
	v_pk_mul_f32 v[148:149], v[62:63], v[144:145] op_sel:[0,1] op_sel_hi:[1,1]
	v_exp_f32_e32 v148, v148
	v_exp_f32_e32 v149, v149
	v_add_f32_e32 v148, 1.0, v148
	v_add_f32_e32 v149, 1.0, v149
	v_rcp_f32_e32 v148, v148
	v_rcp_f32_e32 v149, v149
	s_nop 0
	v_pk_mul_f32 v[62:63], v[62:63], v[148:149]
	v_pk_mul_f32 v[58:59], v[58:59], v[62:63]
	v_pk_mul_f32 v[148:149], v[52:53], v[144:145] op_sel:[0,1] op_sel_hi:[1,1]
	v_exp_f32_e32 v148, v148
	v_exp_f32_e32 v149, v149
	v_add_f32_e32 v148, 1.0, v148
	v_add_f32_e32 v149, 1.0, v149
	v_rcp_f32_e32 v148, v148
	v_rcp_f32_e32 v149, v149
	s_nop 0
	v_pk_mul_f32 v[52:53], v[52:53], v[148:149]
	v_pk_mul_f32 v[48:49], v[48:49], v[52:53]
	v_pk_mul_f32 v[148:149], v[54:55], v[144:145] op_sel:[0,1] op_sel_hi:[1,1]
	v_exp_f32_e32 v148, v148
	v_exp_f32_e32 v149, v149
	v_add_f32_e32 v148, 1.0, v148
	v_add_f32_e32 v149, 1.0, v149
	v_rcp_f32_e32 v148, v148
	v_rcp_f32_e32 v149, v149
	s_nop 0
	v_pk_mul_f32 v[54:55], v[54:55], v[148:149]
	v_pk_mul_f32 v[50:51], v[50:51], v[54:55]
	v_cvt_pk_bf16_f32 v51, v50, v51
	v_cvt_pk_bf16_f32 v50, v48, v49
	v_cvt_pk_bf16_f32 v48, v56, v57
	v_cvt_pk_bf16_f32 v49, v58, v59
	s_mov_b32 s100, 0xb0000
	v_lshl_add_u64 v[52:53], v[118:119], 0, s[100:101]
	global_store_dwordx4 v[52:53], v[48:51], off
	ds_read_b32 v48, v142 offset:576
	s_waitcnt lgkmcnt(0)
; __device__ __forceinline__ u32x4 pack8(const f32x4 a, const f32x4 b) { u32x4 w; w.x = cvt_pk_bf16(a[0], a[1]); w.y = cvt_pk_bf16(a[2], a[3]); w.z = cvt_pk_bf16(b[0], b[1]); w.w = cvt_pk_bf16(b[2], b[3]); return w; }
;     __device__ __forceinline__ void operator()(const f32x4 (&acc)[2][2][4][2], const Unit& u, int wr, int wc, int fr, int fq) const {
;     ...
;                 const int row = u.pm * BM + ai * HALF + wr * 64 + m * 16 + fr;
;                 const float rs = R[ai * HALF + wr * 64 + m * 16 + fr];
;                 bf16_t* ACT = (bf16_t*)(ws + WS_ACT);
;                 f32x4 a[2];
; #pragma unroll
;                 for (int n = 0; n < 2; ++n) {
;                     const f32x4 g = acc[ai][0][m][n] * rs, uu = acc[ai][1][m][n] * rs;
; #pragma unroll
;                     for (int j = 0; j < 4; ++j) a[n][j] = g[j] * __builtin_amdgcn_rcpf(1.0f + __builtin_amdgcn_exp2f(-1.4426950408889634f * g[j])) * uu[j];
;                 }
;                 *(u32x4*)(ACT + (size_t)row * 2816 + u.pn * 128 + wc * 32 + 8 * fq) = pack8(a[0], a[1]);
	v_pk_mul_f32 v[44:45], v[44:45], v[48:49] op_sel_hi:[1,0]
	v_pk_mul_f32 v[46:47], v[46:47], v[48:49] op_sel_hi:[1,0]
	v_pk_mul_f32 v[36:37], v[36:37], v[48:49] op_sel_hi:[1,0]
	v_pk_mul_f32 v[38:39], v[38:39], v[48:49] op_sel_hi:[1,0]
	v_pk_mul_f32 v[40:41], v[40:41], v[48:49] op_sel_hi:[1,0]
	v_pk_mul_f32 v[42:43], v[42:43], v[48:49] op_sel_hi:[1,0]
	v_pk_mul_f32 v[32:33], v[32:33], v[48:49] op_sel_hi:[1,0]
	v_pk_mul_f32 v[34:35], v[34:35], v[48:49] op_sel_hi:[1,0]
	v_pk_mul_f32 v[148:149], v[44:45], v[144:145] op_sel:[0,1] op_sel_hi:[1,1]
	v_exp_f32_e32 v148, v148
	v_exp_f32_e32 v149, v149
	v_add_f32_e32 v148, 1.0, v148
	v_add_f32_e32 v149, 1.0, v149
	v_rcp_f32_e32 v148, v148
	v_rcp_f32_e32 v149, v149
	s_nop 0
	v_pk_mul_f32 v[44:45], v[44:45], v[148:149]
	v_pk_mul_f32 v[40:41], v[40:41], v[44:45]
	v_pk_mul_f32 v[148:149], v[46:47], v[144:145] op_sel:[0,1] op_sel_hi:[1,1]
	v_exp_f32_e32 v148, v148
	v_exp_f32_e32 v149, v149
	v_add_f32_e32 v148, 1.0, v148
	v_add_f32_e32 v149, 1.0, v149
	v_rcp_f32_e32 v148, v148
	v_rcp_f32_e32 v149, v149
	s_nop 0
	v_pk_mul_f32 v[46:47], v[46:47], v[148:149]
	v_pk_mul_f32 v[42:43], v[42:43], v[46:47]
	v_pk_mul_f32 v[148:149], v[36:37], v[144:145] op_sel:[0,1] op_sel_hi:[1,1]
	v_exp_f32_e32 v148, v148
	v_exp_f32_e32 v149, v149
	v_add_f32_e32 v148, 1.0, v148
	v_add_f32_e32 v149, 1.0, v149
	v_rcp_f32_e32 v148, v148
	v_rcp_f32_e32 v149, v149
	s_nop 0
	v_pk_mul_f32 v[36:37], v[36:37], v[148:149]
	v_pk_mul_f32 v[32:33], v[32:33], v[36:37]
	v_pk_mul_f32 v[148:149], v[38:39], v[144:145] op_sel:[0,1] op_sel_hi:[1,1]
	v_exp_f32_e32 v148, v148
	v_exp_f32_e32 v149, v149
	v_add_f32_e32 v148, 1.0, v148
	v_add_f32_e32 v149, 1.0, v149
	v_rcp_f32_e32 v148, v148
	v_rcp_f32_e32 v149, v149
	s_nop 0
	v_pk_mul_f32 v[38:39], v[38:39], v[148:149]
	v_pk_mul_f32 v[34:35], v[34:35], v[38:39]
	v_cvt_pk_bf16_f32 v35, v34, v35
	v_cvt_pk_bf16_f32 v34, v32, v33
	v_cvt_pk_bf16_f32 v32, v40, v41
	v_cvt_pk_bf16_f32 v33, v42, v43
	s_mov_b32 s100, 0xc6000
	v_lshl_add_u64 v[36:37], v[118:119], 0, s[100:101]
	global_store_dwordx4 v[36:37], v[32:35], off
	ds_read_b32 v32, v142 offset:640
	s_waitcnt lgkmcnt(0)
	v_pk_mul_f32 v[28:29], v[28:29], v[32:33] op_sel_hi:[1,0]
	v_pk_mul_f32 v[30:31], v[30:31], v[32:33] op_sel_hi:[1,0]
	v_pk_mul_f32 v[20:21], v[20:21], v[32:33] op_sel_hi:[1,0]
	v_pk_mul_f32 v[22:23], v[22:23], v[32:33] op_sel_hi:[1,0]
	v_pk_mul_f32 v[24:25], v[24:25], v[32:33] op_sel_hi:[1,0]
	v_pk_mul_f32 v[26:27], v[26:27], v[32:33] op_sel_hi:[1,0]
	v_pk_mul_f32 v[16:17], v[16:17], v[32:33] op_sel_hi:[1,0]
	v_pk_mul_f32 v[18:19], v[18:19], v[32:33] op_sel_hi:[1,0]
	v_pk_mul_f32 v[148:149], v[28:29], v[144:145] op_sel:[0,1] op_sel_hi:[1,1]
	v_exp_f32_e32 v148, v148
	v_exp_f32_e32 v149, v149
	v_add_f32_e32 v148, 1.0, v148
	v_add_f32_e32 v149, 1.0, v149
	v_rcp_f32_e32 v148, v148
	v_rcp_f32_e32 v149, v149
	s_nop 0
	v_pk_mul_f32 v[28:29], v[28:29], v[148:149]
	v_pk_mul_f32 v[24:25], v[24:25], v[28:29]
	v_pk_mul_f32 v[148:149], v[30:31], v[144:145] op_sel:[0,1] op_sel_hi:[1,1]
	v_exp_f32_e32 v148, v148
	v_exp_f32_e32 v149, v149
	v_add_f32_e32 v148, 1.0, v148
	v_add_f32_e32 v149, 1.0, v149
	v_rcp_f32_e32 v148, v148
	v_rcp_f32_e32 v149, v149
	s_nop 0
	v_pk_mul_f32 v[30:31], v[30:31], v[148:149]
	v_pk_mul_f32 v[26:27], v[26:27], v[30:31]
	v_pk_mul_f32 v[148:149], v[20:21], v[144:145] op_sel:[0,1] op_sel_hi:[1,1]
	v_exp_f32_e32 v148, v148
	v_exp_f32_e32 v149, v149
	v_add_f32_e32 v148, 1.0, v148
	v_add_f32_e32 v149, 1.0, v149
	v_rcp_f32_e32 v148, v148
	v_rcp_f32_e32 v149, v149
	s_nop 0
	v_pk_mul_f32 v[20:21], v[20:21], v[148:149]
	v_pk_mul_f32 v[16:17], v[16:17], v[20:21]
	v_pk_mul_f32 v[148:149], v[22:23], v[144:145] op_sel:[0,1] op_sel_hi:[1,1]
	v_exp_f32_e32 v148, v148
	v_exp_f32_e32 v149, v149
	v_add_f32_e32 v148, 1.0, v148
	v_add_f32_e32 v149, 1.0, v149
	v_rcp_f32_e32 v148, v148
	v_rcp_f32_e32 v149, v149
	s_nop 0
	v_pk_mul_f32 v[22:23], v[22:23], v[148:149]
	v_pk_mul_f32 v[18:19], v[18:19], v[22:23]
	v_cvt_pk_bf16_f32 v19, v18, v19
	v_cvt_pk_bf16_f32 v18, v16, v17
	v_cvt_pk_bf16_f32 v16, v24, v25
	v_cvt_pk_bf16_f32 v17, v26, v27
	s_mov_b32 s100, 0xdc000
	v_lshl_add_u64 v[20:21], v[118:119], 0, s[100:101]
	global_store_dwordx4 v[20:21], v[16:19], off
	ds_read_b32 v16, v142 offset:704
	s_waitcnt lgkmcnt(0)
	v_pk_mul_f32 v[12:13], v[12:13], v[16:17] op_sel_hi:[1,0]
	v_pk_mul_f32 v[14:15], v[14:15], v[16:17] op_sel_hi:[1,0]
	v_pk_mul_f32 v[4:5], v[4:5], v[16:17] op_sel_hi:[1,0]
	v_pk_mul_f32 v[6:7], v[6:7], v[16:17] op_sel_hi:[1,0]
	v_pk_mul_f32 v[8:9], v[8:9], v[16:17] op_sel_hi:[1,0]
	v_pk_mul_f32 v[10:11], v[10:11], v[16:17] op_sel_hi:[1,0]
	v_pk_mul_f32 v[0:1], v[0:1], v[16:17] op_sel_hi:[1,0]
	v_pk_mul_f32 v[2:3], v[2:3], v[16:17] op_sel_hi:[1,0]
	v_pk_mul_f32 v[148:149], v[12:13], v[144:145] op_sel:[0,1] op_sel_hi:[1,1]
	v_exp_f32_e32 v148, v148
	v_exp_f32_e32 v149, v149
	v_add_f32_e32 v148, 1.0, v148
	v_add_f32_e32 v149, 1.0, v149
	v_rcp_f32_e32 v148, v148
	v_rcp_f32_e32 v149, v149
	s_nop 0
	v_pk_mul_f32 v[12:13], v[12:13], v[148:149]
	v_pk_mul_f32 v[8:9], v[8:9], v[12:13]
	v_pk_mul_f32 v[148:149], v[14:15], v[144:145] op_sel:[0,1] op_sel_hi:[1,1]
	v_exp_f32_e32 v148, v148
	v_exp_f32_e32 v149, v149
	v_add_f32_e32 v148, 1.0, v148
	v_add_f32_e32 v149, 1.0, v149
	v_rcp_f32_e32 v148, v148
	v_rcp_f32_e32 v149, v149
	s_nop 0
	v_pk_mul_f32 v[14:15], v[14:15], v[148:149]
	v_pk_mul_f32 v[10:11], v[10:11], v[14:15]
	v_pk_mul_f32 v[148:149], v[4:5], v[144:145] op_sel:[0,1] op_sel_hi:[1,1]
	v_exp_f32_e32 v148, v148
	v_exp_f32_e32 v149, v149
	v_add_f32_e32 v148, 1.0, v148
	v_add_f32_e32 v149, 1.0, v149
	v_rcp_f32_e32 v148, v148
	v_rcp_f32_e32 v149, v149
	s_nop 0
	v_pk_mul_f32 v[4:5], v[4:5], v[148:149]
	v_pk_mul_f32 v[0:1], v[0:1], v[4:5]
	v_pk_mul_f32 v[148:149], v[6:7], v[144:145] op_sel:[0,1] op_sel_hi:[1,1]
	v_exp_f32_e32 v148, v148
	v_exp_f32_e32 v149, v149
	v_add_f32_e32 v148, 1.0, v148
	v_add_f32_e32 v149, 1.0, v149
	v_rcp_f32_e32 v148, v148
	v_rcp_f32_e32 v149, v149
	s_nop 0
	v_pk_mul_f32 v[6:7], v[6:7], v[148:149]
	v_pk_mul_f32 v[2:3], v[2:3], v[6:7]
	v_cvt_pk_bf16_f32 v3, v2, v3
	v_cvt_pk_bf16_f32 v2, v0, v1
	v_cvt_pk_bf16_f32 v0, v8, v9
	v_cvt_pk_bf16_f32 v1, v10, v11
	s_mov_b32 s100, 0xf2000
	v_lshl_add_u64 v[4:5], v[118:119], 0, s[100:101]
	s_mov_b64 s[0:1], -1
	global_store_dwordx4 v[4:5], v[0:3], off
	s_cbranch_vccnz .LBB0_31
	s_andn2_b64 vcc, exec, s[8:9]
	s_cbranch_vccnz .LBB0_30
	s_barrier
	s_branch .LBB0_30
